# attention: K-fragment LDS reads batched with interleaved QK^T accumulation chains; next-tile K/V prefetch moved behind the QK^T MFMAs
# speedup vs baseline: 1.0071x; 1.0038x over previous
.LBB0_379:
	v_add_u32_e32 v122, v108, v110
	ds_read_b128 v[192:195], v122
	ds_read_b128 v[196:199], v122 offset:4608
	ds_read_b128 v[200:203], v122 offset:32
	ds_read_b128 v[204:207], v122 offset:4640
	ds_read_b128 v[208:211], v122 offset:64
	ds_read_b128 v[212:215], v122 offset:4672
	ds_read_b128 v[216:219], v122 offset:96
	ds_read_b128 v[220:223], v122 offset:4704
	v_add_u32_e32 v127, s95, v97
	s_waitcnt lgkmcnt(7)
	v_mfma_f32_32x32x16_bf16 v[48:63], v[192:195], v[72:75], 0
	ds_read_b64_tr_b16 v[134:135], v167 offset:9216
	ds_read_b64_tr_b16 v[136:137], v167 offset:10368
	s_waitcnt lgkmcnt(8)
	v_mfma_f32_32x32x16_bf16 v[32:47], v[196:199], v[72:75], 0
	ds_read_b64_tr_b16 v[138:139], v167 offset:9792
	ds_read_b64_tr_b16 v[140:141], v167 offset:10944
	s_waitcnt lgkmcnt(9)
	v_mfma_f32_32x32x16_bf16 v[48:63], v[200:203], v[76:79], v[48:63]
	ds_read_b64_tr_b16 v[142:143], v167 offset:11520
	ds_read_b64_tr_b16 v[144:145], v167 offset:12672
	s_waitcnt lgkmcnt(10)
	v_mfma_f32_32x32x16_bf16 v[32:47], v[204:207], v[76:79], v[32:47]
	ds_read_b64_tr_b16 v[146:147], v167 offset:12096
	ds_read_b64_tr_b16 v[148:149], v167 offset:13248
	s_waitcnt lgkmcnt(11)
	v_mfma_f32_32x32x16_bf16 v[48:63], v[208:211], v[84:87], v[48:63]
	ds_read_b64_tr_b16 v[150:151], v167 offset:13824
	ds_read_b64_tr_b16 v[152:153], v167 offset:14976
	s_waitcnt lgkmcnt(12)
	v_mfma_f32_32x32x16_bf16 v[32:47], v[212:215], v[84:87], v[32:47]
	ds_read_b64_tr_b16 v[154:155], v167 offset:14400
	ds_read_b64_tr_b16 v[156:157], v167 offset:15552
	s_waitcnt lgkmcnt(13)
	v_mfma_f32_32x32x16_bf16 v[48:63], v[216:219], v[92:95], v[48:63]
	ds_read_b64_tr_b16 v[158:159], v167 offset:16128
	ds_read_b64_tr_b16 v[160:161], v167 offset:17280
	s_waitcnt lgkmcnt(14)
	v_mfma_f32_32x32x16_bf16 v[32:47], v[220:223], v[92:95], v[32:47]
	ds_read_b64_tr_b16 v[162:163], v167 offset:16704
	ds_read_b64_tr_b16 v[164:165], v167 offset:17856
	s_cbranch_scc1 .Lattn_pf_done
	s_and_b64 vcc, exec, s[56:57]
	s_cbranch_vccz .LBB0_371
	s_lshl_b64 s[66:67], s[80:81], 8
	s_add_u32 s66, s66, s58
	s_addc_u32 s67, s67, s59
	s_mov_b64 s[72:73], -1
	s_cbranch_execz .LBB0_372
	s_branch .LBB0_376

.LBB0_377:
	s_add_u32 s62, s44, s76
	s_addc_u32 s76, s45, s77
	s_add_u32 s72, s44, s74
	s_addc_u32 s73, s45, s75
	s_add_u32 s66, s66, s79
	s_addc_u32 s67, s67, 0
	s_lshl_b64 s[66:67], s[66:67], 1
	s_add_u32 s72, s72, s66
	s_addc_u32 s73, s73, s67
	s_add_u32 s66, s62, s66
	s_addc_u32 s67, s76, s67
	v_lshl_add_u64 v[192:193], s[72:73], 0, v[100:101]
	v_lshl_add_u64 v[192:193], v[192:193], 0, v[128:129]
	v_lshl_add_u64 v[194:195], s[66:67], 0, v[100:101]
	v_lshl_add_u64 v[194:195], v[194:195], 0, v[128:129]
	global_load_dwordx4 v[64:67], v[192:193], off
	global_load_dwordx4 v[68:71], v[194:195], off
	v_lshl_add_u64 v[192:193], s[72:73], 0, v[102:103]
	v_lshl_add_u64 v[192:193], v[192:193], 0, v[128:129]
	v_lshl_add_u64 v[194:195], s[66:67], 0, v[102:103]
	v_lshl_add_u64 v[194:195], v[194:195], 0, v[128:129]
	global_load_dwordx4 v[80:83], v[192:193], off
	global_load_dwordx4 v[88:91], v[194:195], off

.Lattn_pf_done:
	v_cmp_gt_u32_e32 vcc, s9, v127
	s_nop 7
	v_add_u32_e32 v173, 59, v127
	v_cmp_gt_u32_e64 s[98:99], s9, v173
	s_nop 1
	s_and_b64 s[98:99], s[98:99], vcc
	s_cmp_eq_u64 s[98:99], -1
	s_cbranch_scc1 .Lattn_nomask
	s_cmp_eq_u64 s[64:65], 0
	s_cbranch_scc1 .Lattn_nomask
	s_nop 1
	v_cndmask_b32_e32 v118, v189, v48, vcc
	v_cndmask_b32_e64 v48, v48, v118, s[64:65]
	v_add_u32_e32 v118, 1, v127
	v_cmp_gt_u32_e32 vcc, s9, v118
	s_nop 1
	v_cndmask_b32_e32 v118, v189, v49, vcc
	v_cndmask_b32_e64 v49, v49, v118, s[64:65]
	v_add_u32_e32 v118, 2, v127
	v_cmp_gt_u32_e32 vcc, s9, v118
	v_max3_f32 v119, v117, v48, v49
	s_nop 0
	v_cndmask_b32_e32 v118, v189, v50, vcc
	v_cndmask_b32_e64 v50, v50, v118, s[64:65]
	v_add_u32_e32 v118, 3, v127
	v_cmp_gt_u32_e32 vcc, s9, v118
	s_nop 1
	v_cndmask_b32_e32 v118, v189, v51, vcc
	v_cndmask_b32_e64 v118, v51, v118, s[64:65]
	v_max3_f32 v51, v119, v50, v118
	v_add_u32_e32 v119, 8, v127
	v_cmp_gt_u32_e32 vcc, s9, v119
	s_nop 1
	v_cndmask_b32_e32 v119, v189, v52, vcc
	v_cndmask_b32_e64 v52, v52, v119, s[64:65]
	v_add_u32_e32 v119, 9, v127
	v_cmp_gt_u32_e32 vcc, s9, v119
	s_nop 1
	v_cndmask_b32_e32 v119, v189, v53, vcc
	v_cndmask_b32_e64 v53, v53, v119, s[64:65]
	v_add_u32_e32 v119, 10, v127
	v_cmp_gt_u32_e32 vcc, s9, v119
	v_max3_f32 v51, v51, v52, v53
	s_nop 0
	v_cndmask_b32_e32 v119, v189, v54, vcc
	v_cndmask_b32_e64 v54, v54, v119, s[64:65]
	v_add_u32_e32 v119, 11, v127
	v_cmp_gt_u32_e32 vcc, s9, v119
	s_nop 1
	v_cndmask_b32_e32 v119, v189, v55, vcc
	v_cndmask_b32_e64 v119, v55, v119, s[64:65]
	v_add_u32_e32 v55, 16, v127
	v_cmp_gt_u32_e32 vcc, s9, v55
	v_max3_f32 v51, v51, v54, v119
	s_nop 0
	v_cndmask_b32_e32 v55, v189, v56, vcc
	v_cndmask_b32_e64 v121, v56, v55, s[64:65]
	v_add_u32_e32 v55, 17, v127
	v_cmp_gt_u32_e32 vcc, s9, v55
	s_nop 1
	v_cndmask_b32_e32 v55, v189, v57, vcc
	v_cndmask_b32_e64 v120, v57, v55, s[64:65]
	v_add_u32_e32 v55, 18, v127
	v_cmp_gt_u32_e32 vcc, s9, v55
	v_max3_f32 v51, v51, v121, v120
	s_nop 0
	v_cndmask_b32_e32 v55, v189, v58, vcc
	v_cndmask_b32_e64 v122, v58, v55, s[64:65]
	v_add_u32_e32 v55, 19, v127
	v_cmp_gt_u32_e32 vcc, s9, v55
	s_nop 1
	v_cndmask_b32_e32 v55, v189, v59, vcc
	v_cndmask_b32_e64 v123, v59, v55, s[64:65]
	v_add_u32_e32 v55, 24, v127
	v_cmp_gt_u32_e32 vcc, s9, v55
	v_max3_f32 v51, v51, v122, v123
	s_nop 0
	v_cndmask_b32_e32 v55, v189, v60, vcc
	v_cndmask_b32_e64 v60, v60, v55, s[64:65]
	v_add_u32_e32 v55, 25, v127
	v_cmp_gt_u32_e32 vcc, s9, v55
	s_nop 1
	v_cndmask_b32_e32 v55, v189, v61, vcc
	v_cndmask_b32_e64 v61, v61, v55, s[64:65]
	v_add_u32_e32 v55, 26, v127
	v_cmp_gt_u32_e32 vcc, s9, v55
	v_max3_f32 v51, v51, v60, v61
	s_nop 0
	v_cndmask_b32_e32 v55, v189, v62, vcc
	v_cndmask_b32_e64 v62, v62, v55, s[64:65]
	v_add_u32_e32 v55, 27, v127
	v_cmp_gt_u32_e32 vcc, s9, v55
	s_nop 1
	v_cndmask_b32_e32 v55, v189, v63, vcc
	v_cndmask_b32_e64 v63, v63, v55, s[64:65]
	v_add_u32_e32 v55, 32, v127
	v_cmp_gt_u32_e32 vcc, s9, v55
	v_max3_f32 v51, v51, v62, v63
	s_nop 0
	v_cndmask_b32_e32 v55, v189, v32, vcc
	v_cndmask_b32_e64 v124, v32, v55, s[64:65]
	v_add_u32_e32 v32, 33, v127
	v_cmp_gt_u32_e32 vcc, s9, v32
	s_nop 1
	v_cndmask_b32_e32 v32, v189, v33, vcc
	v_cndmask_b32_e64 v125, v33, v32, s[64:65]
	v_add_u32_e32 v33, 34, v127
	v_cmp_gt_u32_e32 vcc, s9, v33
	v_max3_f32 v32, v51, v124, v125
	s_nop 0
	v_cndmask_b32_e32 v33, v189, v34, vcc
	v_cndmask_b32_e64 v126, v34, v33, s[64:65]
	v_add_u32_e32 v33, 35, v127
	v_cmp_gt_u32_e32 vcc, s9, v33
	v_add_u32_e32 v34, 57, v127
	s_nop 0
	v_cndmask_b32_e32 v33, v189, v35, vcc
	v_cndmask_b32_e64 v59, v35, v33, s[64:65]
	v_add_u32_e32 v33, 40, v127
	v_cmp_gt_u32_e32 vcc, s9, v33
	v_max3_f32 v32, v32, v126, v59
	s_nop 0
	v_cndmask_b32_e32 v33, v189, v36, vcc
	v_cndmask_b32_e64 v56, v36, v33, s[64:65]
	v_add_u32_e32 v33, 41, v127
	v_cmp_gt_u32_e32 vcc, s9, v33
	s_nop 1
	v_cndmask_b32_e32 v33, v189, v37, vcc
	v_cndmask_b32_e64 v57, v37, v33, s[64:65]
	v_add_u32_e32 v33, 42, v127
	v_cmp_gt_u32_e32 vcc, s9, v33
	v_max3_f32 v32, v32, v56, v57
	s_nop 0
	v_cndmask_b32_e32 v33, v189, v38, vcc
	v_cndmask_b32_e64 v58, v38, v33, s[64:65]
	v_add_u32_e32 v33, 43, v127
	v_cmp_gt_u32_e32 vcc, s9, v33
	s_nop 1
	v_cndmask_b32_e32 v33, v189, v39, vcc
	v_cndmask_b32_e64 v55, v39, v33, s[64:65]
	v_add_u32_e32 v33, 48, v127
	v_cmp_gt_u32_e32 vcc, s9, v33
	v_max3_f32 v32, v32, v58, v55
	s_nop 0
	v_cndmask_b32_e32 v33, v189, v40, vcc
	v_cndmask_b32_e64 v37, v40, v33, s[64:65]
	v_add_u32_e32 v33, 49, v127
	v_cmp_gt_u32_e32 vcc, s9, v33
	s_nop 1
	v_cndmask_b32_e32 v33, v189, v41, vcc
	v_cndmask_b32_e64 v38, v41, v33, s[64:65]
	v_add_u32_e32 v33, 50, v127
	v_cmp_gt_u32_e32 vcc, s9, v33
	v_max3_f32 v32, v32, v37, v38
	s_nop 0
	v_cndmask_b32_e32 v33, v189, v42, vcc
	v_cndmask_b32_e64 v39, v42, v33, s[64:65]
	v_add_u32_e32 v33, 51, v127
	v_cmp_gt_u32_e32 vcc, s9, v33
	s_nop 1
	v_cndmask_b32_e32 v33, v189, v43, vcc
	v_cndmask_b32_e64 v36, v43, v33, s[64:65]
	v_add_u32_e32 v33, 56, v127
	v_cmp_gt_u32_e32 vcc, s9, v33
	v_max3_f32 v32, v32, v39, v36
	s_nop 0
	v_cndmask_b32_e32 v33, v189, v44, vcc
	v_cmp_gt_u32_e32 vcc, s9, v34
	v_cndmask_b32_e64 v33, v44, v33, s[64:65]
	s_nop 0
	v_cndmask_b32_e32 v34, v189, v45, vcc
	v_cndmask_b32_e64 v34, v45, v34, s[64:65]
	v_max3_f32 v40, v32, v33, v34
	v_add_u32_e32 v32, 58, v127
	v_cmp_gt_u32_e32 vcc, s9, v32
	s_nop 1
	v_cndmask_b32_e32 v32, v189, v46, vcc
	v_cndmask_b32_e64 v35, v46, v32, s[64:65]
	v_add_u32_e32 v32, 59, v127
	v_cmp_gt_u32_e32 vcc, s9, v32
	s_nop 1
	v_cndmask_b32_e32 v32, v189, v47, vcc
	v_cndmask_b32_e64 v32, v47, v32, s[64:65]
	v_max3_f32 v40, v40, v35, v32
